# diff attention main loop: V-fragment LDS reads software-pipelined over 8 rotating registers (no per-pair lgkmcnt(0))
# speedup vs baseline: 1.0084x; 1.0038x over previous
.LBB0_1695:
	s_waitcnt vmcnt(6)
	ds_write_b128 v196, v[48:51]
	s_waitcnt vmcnt(6)
	ds_write_b128 v197, v[52:55]
	s_waitcnt vmcnt(5)
	ds_write_b128 v198, v[56:59]
	s_waitcnt vmcnt(3)
	ds_write_b128 v199, v[60:63]
	s_waitcnt vmcnt(3)
	ds_write_b128 v200, v[64:67] offset:17408
	s_waitcnt vmcnt(2)
	ds_write_b128 v201, v[68:71] offset:17408
	s_waitcnt vmcnt(0)
	ds_write_b128 v202, v[72:75] offset:17408
	s_waitcnt vmcnt(0)
	ds_write_b128 v203, v[76:79] offset:17408
	s_waitcnt lgkmcnt(0)
	s_barrier
	ds_read_b128 v[48:51], v195
	ds_read_b128 v[52:55], v195 offset:64
	ds_read_b128 v[60:63], v195 offset:4352
	ds_read_b128 v[64:67], v195 offset:4416
	ds_read_b128 v[72:75], v195 offset:8704
	ds_read_b128 v[76:79], v195 offset:8768
	s_waitcnt lgkmcnt(5)
	v_mfma_f32_16x16x32_bf16 v[56:59], v[48:51], v[8:11], 0
	ds_read_b128 v[116:119], v195 offset:13056
	ds_read_b128 v[120:123], v195 offset:13120
	v_mfma_f32_16x16x32_bf16 v[48:51], v[48:51], v[12:15], 0
	s_waitcnt lgkmcnt(5)
	v_mfma_f32_16x16x32_bf16 v[68:71], v[60:63], v[8:11], 0
	v_mfma_f32_16x16x32_bf16 v[60:63], v[60:63], v[12:15], 0
	s_waitcnt lgkmcnt(3)
	v_mfma_f32_16x16x32_bf16 v[112:115], v[72:75], v[8:11], 0
	v_mfma_f32_16x16x32_bf16 v[72:75], v[72:75], v[12:15], 0
	v_mfma_f32_16x16x32_bf16 v[154:157], v[52:55], v[0:3], v[56:59]
	v_mfma_f32_16x16x32_bf16 v[204:207], v[52:55], v[4:7], v[48:51]
	v_lshl_add_u64 v[52:53], v[144:145], 0, s[46:47]
	s_nop 0
	v_lshl_add_u64 v[56:57], v[146:147], 0, s[46:47]
	global_load_dwordx4 v[52:55], v[52:53], off
	v_lshl_add_u64 v[48:49], v[142:143], 0, s[46:47]
	v_mfma_f32_16x16x32_bf16 v[162:165], v[64:67], v[0:3], v[68:71]
	global_load_dwordx4 v[48:51], v[48:49], off
	s_nop 0
	global_load_dwordx4 v[56:59], v[56:57], off
	v_mfma_f32_16x16x32_bf16 v[208:211], v[64:67], v[4:7], v[60:63]
	v_lshl_add_u64 v[64:65], v[134:135], 0, s[46:47]
	v_lshl_add_u64 v[68:69], v[136:137], 0, s[46:47]
	global_load_dwordx4 v[64:67], v[64:65], off
	v_lshl_add_u64 v[60:61], v[148:149], 0, s[46:47]
	s_waitcnt lgkmcnt(2)
	v_mfma_f32_16x16x32_bf16 v[112:115], v[76:79], v[0:3], v[112:115]
	global_load_dwordx4 v[60:63], v[60:61], off
	s_nop 0
	global_load_dwordx4 v[68:71], v[68:69], off
	v_mfma_f32_16x16x32_bf16 v[212:215], v[76:79], v[4:7], v[72:75]
	v_lshl_add_u64 v[76:77], v[140:141], 0, s[46:47]
	global_load_dwordx4 v[76:79], v[76:77], off
	s_nop 0
	v_lshl_add_u64 v[72:73], v[138:139], 0, s[46:47]
	global_load_dwordx4 v[72:75], v[72:73], off
	s_waitcnt lgkmcnt(1)
	v_mfma_f32_16x16x32_bf16 v[150:153], v[116:119], v[8:11], 0
	v_mfma_f32_16x16x32_bf16 v[116:119], v[116:119], v[12:15], 0
	s_waitcnt lgkmcnt(0)
	v_mfma_f32_16x16x32_bf16 v[178:181], v[120:123], v[0:3], v[150:153]
	s_nop 4
	v_mov_b32_e32 v150, v194
	v_mov_b32_e32 v151, v193
	v_mfma_f32_16x16x32_bf16 v[120:123], v[120:123], v[4:7], v[116:119]
	s_nop 2
	v_max3_f32 v116, v154, s39, v155
	v_max3_f32 v116, v116, v156, v157
	v_max3_f32 v116, v116, v162, v163
	v_max3_f32 v116, v116, v164, v165
	v_max3_f32 v116, v116, v112, v113
	v_max3_f32 v116, v116, v114, v115
	v_max3_f32 v116, v116, v178, v179
	v_max3_f32 v116, v116, v180, v181
	v_mov_b32_e32 v117, v116
	s_nop 1
	v_permlane16_swap_b32_e32 v116, v117
	v_max_f32_e32 v117, v117, v117
	v_max_f32_e32 v116, v116, v116
	v_max_f32_e32 v116, v116, v117
	v_mov_b32_e32 v117, v116
	s_nop 1
	v_permlane32_swap_b32_e32 v116, v117
	v_max3_f32 v193, v151, v116, v117
	v_sub_f32_e32 v117, v154, v193
	v_mul_f32_e32 v117, 0x3fb8aa3b, v117
	v_sub_f32_e32 v116, v151, v193
	v_exp_f32_e32 v151, v117
	v_sub_f32_e32 v117, v155, v193
	v_mul_f32_e32 v117, 0x3fb8aa3b, v117
	v_exp_f32_e32 v153, v117
	v_sub_f32_e32 v117, v156, v193
	v_mul_f32_e32 v117, 0x3fb8aa3b, v117
	v_exp_f32_e32 v155, v117
	v_sub_f32_e32 v117, v157, v193
	v_mul_f32_e32 v117, 0x3fb8aa3b, v117
	v_exp_f32_e32 v157, v117
	v_sub_f32_e32 v117, v162, v193
	v_mul_f32_e32 v117, 0x3fb8aa3b, v117
	v_exp_f32_e32 v159, v117
	v_sub_f32_e32 v117, v163, v193
	v_mul_f32_e32 v117, 0x3fb8aa3b, v117
	v_exp_f32_e32 v161, v117
	v_sub_f32_e32 v117, v164, v193
	v_sub_f32_e32 v112, v112, v193
	v_max3_f32 v152, v204, s39, v205
	v_mul_f32_e32 v117, 0x3fb8aa3b, v117
	v_mul_f32_e32 v112, 0x3fb8aa3b, v112
	v_max3_f32 v152, v152, v206, v207
	v_exp_f32_e32 v163, v117
	v_sub_f32_e32 v117, v165, v193
	v_exp_f32_e32 v165, v112
	v_sub_f32_e32 v112, v113, v193
	v_max3_f32 v152, v152, v208, v209
	v_mul_f32_e32 v112, 0x3fb8aa3b, v112
	v_max3_f32 v152, v152, v210, v211
	v_exp_f32_e32 v169, v112
	v_sub_f32_e32 v112, v114, v193
	v_max3_f32 v152, v152, v212, v213
	v_mul_f32_e32 v112, 0x3fb8aa3b, v112
	v_max3_f32 v152, v152, v214, v215
	v_exp_f32_e32 v171, v112
	v_sub_f32_e32 v112, v115, v193
	v_max3_f32 v152, v152, v120, v121
	v_mul_f32_e32 v112, 0x3fb8aa3b, v112
	v_max3_f32 v152, v152, v122, v123
	v_exp_f32_e32 v173, v112
	v_sub_f32_e32 v112, v178, v193
	v_mov_b32_e32 v154, v152
	v_mul_f32_e32 v112, 0x3fb8aa3b, v112
	s_nop 0
	v_permlane16_swap_b32_e32 v152, v154
	v_exp_f32_e32 v175, v112
	v_sub_f32_e32 v112, v179, v193
	v_max_f32_e32 v154, v154, v154
	v_max_f32_e32 v152, v152, v152
	v_mul_f32_e32 v116, 0x3fb8aa3b, v116
	v_mul_f32_e32 v112, 0x3fb8aa3b, v112
	v_max_f32_e32 v152, v152, v154
	v_exp_f32_e32 v177, v112
	v_sub_f32_e32 v112, v180, v193
	v_exp_f32_e32 v216, v116
	v_mov_b32_e32 v154, v152
	v_mul_f32_e32 v112, 0x3fb8aa3b, v112
	s_nop 0
	v_permlane32_swap_b32_e32 v152, v154
	v_exp_f32_e32 v179, v112
	v_sub_f32_e32 v112, v181, v193
	v_max3_f32 v194, v150, v152, v154
	v_mul_f32_e32 v112, 0x3fb8aa3b, v112
	v_sub_f32_e32 v150, v150, v194
	v_exp_f32_e32 v181, v112
	v_pk_mul_f32 v[110:111], v[110:111], v[216:217] op_sel_hi:[1,0]
	v_pk_mul_f32 v[108:109], v[108:109], v[216:217] op_sel_hi:[1,0]
	v_pk_mul_f32 v[106:107], v[106:107], v[216:217] op_sel_hi:[1,0]
	v_pk_mul_f32 v[104:105], v[104:105], v[216:217] op_sel_hi:[1,0]
	v_pk_mul_f32 v[102:103], v[102:103], v[216:217] op_sel_hi:[1,0]
	v_pk_mul_f32 v[100:101], v[100:101], v[216:217] op_sel_hi:[1,0]
	v_pk_mul_f32 v[94:95], v[94:95], v[216:217] op_sel_hi:[1,0]
	v_pk_mul_f32 v[92:93], v[92:93], v[216:217] op_sel_hi:[1,0]
	v_pk_mul_f32 v[90:91], v[90:91], v[216:217] op_sel_hi:[1,0]
	v_pk_mul_f32 v[88:89], v[88:89], v[216:217] op_sel_hi:[1,0]
	v_pk_mul_f32 v[86:87], v[86:87], v[216:217] op_sel_hi:[1,0]
	v_pk_mul_f32 v[84:85], v[84:85], v[216:217] op_sel_hi:[1,0]
	v_pk_mul_f32 v[82:83], v[82:83], v[216:217] op_sel_hi:[1,0]
	v_pk_mul_f32 v[80:81], v[80:81], v[216:217] op_sel_hi:[1,0]
	v_pk_mul_f32 v[114:115], v[98:99], v[216:217] op_sel_hi:[1,0]
	v_pk_mul_f32 v[112:113], v[96:97], v[216:217] op_sel_hi:[1,0]
	v_mul_f32_e32 v217, 0x3fb8aa3b, v150
	v_sub_f32_e32 v150, v204, v194
	v_mul_f32_e32 v150, 0x3fb8aa3b, v150
	v_exp_f32_e32 v150, v150
	v_cvt_pk_bf16_f32 v116, v151, v153
	v_sub_f32_e32 v152, v205, v194
	v_mul_f32_e32 v152, 0x3fb8aa3b, v152
	v_pk_add_f32 v[204:205], v[150:151], 0 op_sel_hi:[1,0]
	v_sub_f32_e32 v151, v210, v194
	v_sub_f32_e32 v154, v206, v194
	v_mul_f32_e32 v151, 0x3fb8aa3b, v151
	v_exp_f32_e32 v152, v152
	v_mul_f32_e32 v154, 0x3fb8aa3b, v154
	v_sub_f32_e32 v156, v207, v194
	v_exp_f32_e32 v162, v151
	v_sub_f32_e32 v151, v211, v194
	v_exp_f32_e32 v154, v154
	v_mul_f32_e32 v156, 0x3fb8aa3b, v156
	v_sub_f32_e32 v158, v208, v194
	v_mul_f32_e32 v151, 0x3fb8aa3b, v151
	v_exp_f32_e32 v156, v156
	v_mul_f32_e32 v158, 0x3fb8aa3b, v158
	v_sub_f32_e32 v160, v209, v194
	v_exp_f32_e32 v166, v151
	v_sub_f32_e32 v151, v212, v194
	v_exp_f32_e32 v158, v158
	v_mul_f32_e32 v160, 0x3fb8aa3b, v160
	v_mul_f32_e32 v151, 0x3fb8aa3b, v151
	v_sub_f32_e32 v120, v120, v194
	v_exp_f32_e32 v160, v160
	v_pk_add_f32 v[204:205], v[152:153], v[204:205]
	v_exp_f32_e32 v164, v151
	v_sub_f32_e32 v151, v213, v194
	v_mul_f32_e32 v120, 0x3fb8aa3b, v120
	v_mul_f32_e32 v117, 0x3fb8aa3b, v117
	v_pk_add_f32 v[204:205], v[154:155], v[204:205]
	v_mul_f32_e32 v151, 0x3fb8aa3b, v151
	v_exp_f32_e32 v174, v120
	v_sub_f32_e32 v120, v121, v194
	v_exp_f32_e32 v167, v117
	v_pk_add_f32 v[204:205], v[156:157], v[204:205]
	v_exp_f32_e32 v168, v151
	v_sub_f32_e32 v151, v214, v194
	v_mul_f32_e32 v120, 0x3fb8aa3b, v120
	v_pk_add_f32 v[204:205], v[158:159], v[204:205]
	v_mul_f32_e32 v151, 0x3fb8aa3b, v151
	v_exp_f32_e32 v176, v120
	v_sub_f32_e32 v120, v122, v194
	v_pk_add_f32 v[204:205], v[160:161], v[204:205]
	v_exp_f32_e32 v170, v151
	v_sub_f32_e32 v151, v215, v194
	v_mul_f32_e32 v120, 0x3fb8aa3b, v120
	v_mul_f32_e32 v151, 0x3fb8aa3b, v151
	v_exp_f32_e32 v178, v120
	v_sub_f32_e32 v120, v123, v194
	v_pk_add_f32 v[122:123], v[162:163], v[204:205]
	v_exp_f32_e32 v172, v151
	v_pk_add_f32 v[122:123], v[166:167], v[122:123]
	v_mul_f32_e32 v120, 0x3fb8aa3b, v120
	v_pk_add_f32 v[122:123], v[164:165], v[122:123]
	v_exp_f32_e32 v180, v120
	v_pk_add_f32 v[122:123], v[168:169], v[122:123]
	v_exp_f32_e32 v120, v217
	v_pk_add_f32 v[122:123], v[170:171], v[122:123]
	v_mov_b32_e32 v121, v216
	v_pk_add_f32 v[122:123], v[172:173], v[122:123]
	v_cvt_pk_bf16_f32 v96, v165, v169
	v_pk_add_f32 v[122:123], v[174:175], v[122:123]
	v_cvt_pk_bf16_f32 v97, v171, v173
	v_pk_add_f32 v[122:123], v[176:177], v[122:123]
	v_cvt_pk_bf16_f32 v98, v175, v177
	v_pk_add_f32 v[122:123], v[178:179], v[122:123]
	v_cvt_pk_bf16_f32 v99, v179, v181
	v_pk_add_f32 v[122:123], v[180:181], v[122:123]
	v_pk_mul_f32 v[46:47], v[46:47], v[120:121] op_sel_hi:[1,0]
	v_pk_fma_f32 v[132:133], v[132:133], v[120:121], v[122:123]
	v_pk_mul_f32 v[44:45], v[44:45], v[120:121] op_sel_hi:[1,0]
	v_pk_mul_f32 v[42:43], v[42:43], v[120:121] op_sel_hi:[1,0]
	v_pk_mul_f32 v[40:41], v[40:41], v[120:121] op_sel_hi:[1,0]
	v_pk_mul_f32 v[34:35], v[34:35], v[120:121] op_sel_hi:[1,0]
	v_pk_mul_f32 v[32:33], v[32:33], v[120:121] op_sel_hi:[1,0]
	v_pk_mul_f32 v[30:31], v[30:31], v[120:121] op_sel_hi:[1,0]
	v_pk_mul_f32 v[28:29], v[28:29], v[120:121] op_sel_hi:[1,0]
	v_pk_mul_f32 v[26:27], v[26:27], v[120:121] op_sel_hi:[1,0]
	v_pk_mul_f32 v[24:25], v[24:25], v[120:121] op_sel_hi:[1,0]
	v_pk_mul_f32 v[22:23], v[22:23], v[120:121] op_sel_hi:[1,0]
	v_pk_mul_f32 v[20:21], v[20:21], v[120:121] op_sel_hi:[1,0]
	v_pk_mul_f32 v[38:39], v[38:39], v[120:121] op_sel_hi:[1,0]
	v_pk_mul_f32 v[36:37], v[36:37], v[120:121] op_sel_hi:[1,0]
	v_pk_mul_f32 v[18:19], v[18:19], v[120:121] op_sel_hi:[1,0]
	v_pk_mul_f32 v[16:17], v[16:17], v[120:121] op_sel_hi:[1,0]
	v_cvt_pk_bf16_f32 v117, v155, v157
	v_cvt_pk_bf16_f32 v118, v159, v161
	v_cvt_pk_bf16_f32 v119, v163, v167
	v_cvt_pk_bf16_f32 v120, v150, v152
	v_cvt_pk_bf16_f32 v121, v154, v156
	v_cvt_pk_bf16_f32 v122, v158, v160
	v_cvt_pk_bf16_f32 v123, v162, v166
	v_cvt_pk_bf16_f32 v150, v164, v168
	v_cvt_pk_bf16_f32 v151, v170, v172
	v_cvt_pk_bf16_f32 v152, v174, v176
	v_cvt_pk_bf16_f32 v153, v178, v180
	ds_read2_b64 v[218:221], v192 offset0:128 offset1:132
	ds_read2_b64 v[222:225], v191 offset0:128 offset1:132
	ds_read2_b64 v[226:229], v190 offset0:160 offset1:164
	ds_read2_b64 v[230:233], v189 offset0:192 offset1:196
	ds_read2_b64 v[234:237], v188 offset1:4
	ds_read2_b64 v[238:241], v187 offset0:32 offset1:36
	ds_read2_b64 v[242:245], v186 offset0:64 offset1:68
	ds_read2_b64 v[246:249], v128 offset0:96 offset1:100
	s_add_i32 s16, s16, -1
	v_lshl_add_u64 v[134:135], v[134:135], 0, s[56:57]
	v_lshl_add_u64 v[136:137], v[136:137], 0, s[56:57]
	v_lshl_add_u64 v[138:139], v[138:139], 0, s[56:57]
	v_lshl_add_u64 v[140:141], v[140:141], 0, s[56:57]
	v_lshl_add_u64 v[142:143], v[142:143], 0, s[54:55]
	v_lshl_add_u64 v[144:145], v[144:145], 0, s[54:55]
	v_lshl_add_u64 v[146:147], v[146:147], 0, s[54:55]
	v_lshl_add_u64 v[148:149], v[148:149], 0, s[54:55]
	s_cmp_lg_u32 s16, 0
	s_waitcnt lgkmcnt(7)
	v_mfma_f32_16x16x32_bf16 v[108:111], v[218:221], v[116:119], v[108:111]
	v_mfma_f32_16x16x32_bf16 v[44:47], v[218:221], v[120:123], v[44:47]
	ds_read2_b64 v[218:221], v192 offset0:136 offset1:140
	s_waitcnt lgkmcnt(7)
	v_mfma_f32_16x16x32_bf16 v[104:107], v[222:225], v[116:119], v[104:107]
	v_mfma_f32_16x16x32_bf16 v[40:43], v[222:225], v[120:123], v[40:43]
	ds_read2_b64 v[222:225], v191 offset0:136 offset1:140
	s_waitcnt lgkmcnt(7)
	v_mfma_f32_16x16x32_bf16 v[100:103], v[226:229], v[116:119], v[100:103]
	v_mfma_f32_16x16x32_bf16 v[32:35], v[226:229], v[120:123], v[32:35]
	ds_read2_b64 v[226:229], v190 offset0:168 offset1:172
	s_waitcnt lgkmcnt(7)
	v_mfma_f32_16x16x32_bf16 v[92:95], v[230:233], v[116:119], v[92:95]
	v_mfma_f32_16x16x32_bf16 v[28:31], v[230:233], v[120:123], v[28:31]
	ds_read2_b64 v[230:233], v189 offset0:200 offset1:204
	s_waitcnt lgkmcnt(7)
	v_mfma_f32_16x16x32_bf16 v[88:91], v[234:237], v[116:119], v[88:91]
	v_mfma_f32_16x16x32_bf16 v[24:27], v[234:237], v[120:123], v[24:27]
	ds_read2_b64 v[234:237], v188 offset0:8 offset1:12
	s_waitcnt lgkmcnt(7)
	v_mfma_f32_16x16x32_bf16 v[84:87], v[238:241], v[116:119], v[84:87]
	v_mfma_f32_16x16x32_bf16 v[20:23], v[238:241], v[120:123], v[20:23]
	ds_read2_b64 v[238:241], v187 offset0:40 offset1:44
	s_waitcnt lgkmcnt(7)
	v_mfma_f32_16x16x32_bf16 v[80:83], v[242:245], v[116:119], v[80:83]
	v_mfma_f32_16x16x32_bf16 v[36:39], v[242:245], v[120:123], v[36:39]
	ds_read2_b64 v[242:245], v186 offset0:72 offset1:76
	s_waitcnt lgkmcnt(7)
	v_mfma_f32_16x16x32_bf16 v[112:115], v[246:249], v[116:119], v[112:115]
	v_mfma_f32_16x16x32_bf16 v[16:19], v[246:249], v[120:123], v[16:19]
	ds_read2_b64 v[246:249], v128 offset0:104 offset1:108
	s_waitcnt lgkmcnt(7)
	v_mfma_f32_16x16x32_bf16 v[108:111], v[218:221], v[96:99], v[108:111]
	v_mfma_f32_16x16x32_bf16 v[44:47], v[218:221], v[150:153], v[44:47]
	s_waitcnt lgkmcnt(6)
	v_mfma_f32_16x16x32_bf16 v[104:107], v[222:225], v[96:99], v[104:107]
	v_mfma_f32_16x16x32_bf16 v[40:43], v[222:225], v[150:153], v[40:43]
	s_waitcnt lgkmcnt(5)
	v_mfma_f32_16x16x32_bf16 v[100:103], v[226:229], v[96:99], v[100:103]
	v_mfma_f32_16x16x32_bf16 v[32:35], v[226:229], v[150:153], v[32:35]
	s_waitcnt lgkmcnt(4)
	v_mfma_f32_16x16x32_bf16 v[92:95], v[230:233], v[96:99], v[92:95]
	v_mfma_f32_16x16x32_bf16 v[28:31], v[230:233], v[150:153], v[28:31]
	s_waitcnt lgkmcnt(3)
	v_mfma_f32_16x16x32_bf16 v[88:91], v[234:237], v[96:99], v[88:91]
	v_mfma_f32_16x16x32_bf16 v[24:27], v[234:237], v[150:153], v[24:27]
	s_waitcnt lgkmcnt(0)
	s_barrier
	v_mfma_f32_16x16x32_bf16 v[84:87], v[238:241], v[96:99], v[84:87]
	v_mfma_f32_16x16x32_bf16 v[20:23], v[238:241], v[150:153], v[20:23]
	v_mfma_f32_16x16x32_bf16 v[80:83], v[242:245], v[96:99], v[80:83]
	v_mfma_f32_16x16x32_bf16 v[36:39], v[242:245], v[150:153], v[36:39]
	v_mfma_f32_16x16x32_bf16 v[96:99], v[246:249], v[96:99], v[112:115]
	v_mfma_f32_16x16x32_bf16 v[16:19], v[246:249], v[150:153], v[16:19]
	s_cbranch_scc1 .LBB0_1695
	s_waitcnt vmcnt(6)
	ds_write_b128 v196, v[48:51]
	ds_write_b128 v197, v[52:55]
	s_waitcnt vmcnt(5)
	ds_write_b128 v198, v[56:59]
	s_waitcnt vmcnt(3)
	ds_write_b128 v199, v[60:63]
	ds_write_b128 v200, v[64:67] offset:17408
	s_waitcnt vmcnt(2)
	ds_write_b128 v201, v[68:71] offset:17408
	s_waitcnt vmcnt(0)
	ds_write_b128 v202, v[72:75] offset:17408
	ds_write_b128 v203, v[76:79] offset:17408
	s_waitcnt lgkmcnt(0)
	s_barrier
	ds_read_b128 v[48:51], v195
	ds_read_b128 v[56:59], v195 offset:4352
	ds_read_b128 v[64:67], v195 offset:8704
	ds_read_b128 v[72:75], v195 offset:13056
	s_waitcnt lgkmcnt(3)
	v_mfma_f32_16x16x32_bf16 v[52:55], v[48:51], v[8:11], 0
	s_waitcnt lgkmcnt(2)
	v_mfma_f32_16x16x32_bf16 v[60:63], v[56:59], v[8:11], 0
	s_waitcnt lgkmcnt(1)
	v_mfma_f32_16x16x32_bf16 v[68:71], v[64:67], v[8:11], 0
	s_waitcnt lgkmcnt(0)
	v_mfma_f32_16x16x32_bf16 v[76:79], v[72:75], v[8:11], 0
	ds_read_b128 v[8:11], v195 offset:64
	v_mfma_f32_16x16x32_bf16 v[48:51], v[48:51], v[12:15], 0
	s_waitcnt lgkmcnt(0)
	v_mfma_f32_16x16x32_bf16 v[52:55], v[8:11], v[0:3], v[52:55]
	v_mfma_f32_16x16x32_bf16 v[48:51], v[8:11], v[4:7], v[48:51]
	ds_read_b128 v[8:11], v195 offset:4416
	v_mfma_f32_16x16x32_bf16 v[56:59], v[56:59], v[12:15], 0
	v_mfma_f32_16x16x32_bf16 v[64:67], v[64:67], v[12:15], 0
	v_mfma_f32_16x16x32_bf16 v[72:75], v[72:75], v[12:15], 0
	s_waitcnt lgkmcnt(0)
	v_mfma_f32_16x16x32_bf16 v[60:63], v[8:11], v[0:3], v[60:63]
	v_mfma_f32_16x16x32_bf16 v[12:15], v[8:11], v[4:7], v[56:59]
	ds_read_b128 v[8:11], v195 offset:8768
	s_waitcnt lgkmcnt(0)
	v_mfma_f32_16x16x32_bf16 v[56:59], v[8:11], v[0:3], v[68:71]
	v_mfma_f32_16x16x32_bf16 v[8:11], v[8:11], v[4:7], v[64:67]
	s_nop 2
	ds_read_b128 v[64:67], v195 offset:13120
	s_waitcnt lgkmcnt(0)
	v_mfma_f32_16x16x32_bf16 v[68:71], v[64:67], v[0:3], v[76:79]
	v_mfma_f32_16x16x32_bf16 v[0:3], v[64:67], v[4:7], v[72:75]
	v_max3_f32 v4, v52, s39, v53
	v_max3_f32 v4, v4, v54, v55
	v_max3_f32 v4, v4, v60, v61
	v_max3_f32 v4, v4, v62, v63
	v_max3_f32 v4, v4, v56, v57
	v_max3_f32 v4, v4, v58, v59
	s_nop 0
	v_max3_f32 v4, v4, v68, v69
	v_max3_f32 v4, v4, v70, v71
	v_mov_b32_e32 v5, v4
	s_nop 1
	v_permlane16_swap_b32_e32 v4, v5
	v_max_f32_e32 v5, v5, v5
	v_max_f32_e32 v4, v4, v4
	v_max_f32_e32 v4, v4, v5
	v_mov_b32_e32 v5, v4
	s_nop 1
	v_permlane32_swap_b32_e32 v4, v5
	v_max3_f32 v4, v193, v4, v5
	v_sub_f32_e32 v7, v53, v4
	v_mul_f32_e32 v7, 0x3fb8aa3b, v7
	v_exp_f32_e32 v113, v7
	v_sub_f32_e32 v7, v54, v4
	v_mul_f32_e32 v7, 0x3fb8aa3b, v7
	v_exp_f32_e32 v114, v7
	v_sub_f32_e32 v7, v55, v4
	v_mul_f32_e32 v7, 0x3fb8aa3b, v7
	v_exp_f32_e32 v115, v7
	v_sub_f32_e32 v7, v60, v4
	v_mul_f32_e32 v7, 0x3fb8aa3b, v7
	v_exp_f32_e32 v116, v7
	v_sub_f32_e32 v7, v61, v4
	v_mul_f32_e32 v7, 0x3fb8aa3b, v7
	v_exp_f32_e32 v117, v7
	v_sub_f32_e32 v7, v62, v4
	v_mul_f32_e32 v7, 0x3fb8aa3b, v7
	v_sub_f32_e32 v5, v52, v4
	v_exp_f32_e32 v118, v7
	v_sub_f32_e32 v7, v63, v4
	v_mul_f32_e32 v5, 0x3fb8aa3b, v5
	v_mul_f32_e32 v7, 0x3fb8aa3b, v7
	v_exp_f32_e32 v112, v5
	v_exp_f32_e32 v119, v7
	v_sub_f32_e32 v7, v56, v4
	v_mul_f32_e32 v7, 0x3fb8aa3b, v7
	v_exp_f32_e32 v120, v7
	v_sub_f32_e32 v7, v57, v4
	v_mul_f32_e32 v7, 0x3fb8aa3b, v7
	v_add_f32_e32 v6, 0, v112
	v_exp_f32_e32 v57, v7
	v_sub_f32_e32 v7, v58, v4
	v_add_f32_e32 v6, v113, v6
	v_mul_f32_e32 v7, 0x3fb8aa3b, v7
	v_add_f32_e32 v6, v114, v6
	v_exp_f32_e32 v58, v7
	v_sub_f32_e32 v7, v59, v4
	v_add_f32_e32 v6, v115, v6
	v_mul_f32_e32 v7, 0x3fb8aa3b, v7
	v_add_f32_e32 v6, v116, v6
	v_exp_f32_e32 v59, v7
	v_sub_f32_e32 v7, v68, v4
	v_add_f32_e32 v6, v117, v6
	v_mul_f32_e32 v7, 0x3fb8aa3b, v7
	v_add_f32_e32 v6, v118, v6
	v_exp_f32_e32 v121, v7
	v_sub_f32_e32 v7, v69, v4
	v_add_f32_e32 v6, v119, v6
	v_mul_f32_e32 v7, 0x3fb8aa3b, v7
	v_add_f32_e32 v6, v120, v6
	v_exp_f32_e32 v122, v7
	v_sub_f32_e32 v7, v70, v4
	v_sub_f32_e32 v5, v193, v4
	v_add_f32_e32 v6, v57, v6
	v_mul_f32_e32 v7, 0x3fb8aa3b, v7
	v_sub_f32_e32 v4, v71, v4
	v_add_f32_e32 v6, v58, v6
	v_exp_f32_e32 v123, v7
	v_mul_f32_e32 v4, 0x3fb8aa3b, v4
	v_mul_f32_e32 v5, 0x3fb8aa3b, v5
	v_add_f32_e32 v6, v59, v6
	v_exp_f32_e32 v134, v4
	v_add_f32_e32 v6, v121, v6
	v_exp_f32_e32 v56, v5
	v_add_f32_e32 v4, v122, v6
	v_add_f32_e32 v4, v123, v4
	v_add_f32_e32 v135, v134, v4
	v_fmac_f32_e32 v135, v133, v56
	v_pk_mul_f32 v[110:111], v[110:111], v[56:57] op_sel_hi:[1,0]
	v_pk_mul_f32 v[108:109], v[108:109], v[56:57] op_sel_hi:[1,0]
	v_pk_mul_f32 v[78:79], v[106:107], v[56:57] op_sel_hi:[1,0]
	v_pk_mul_f32 v[76:77], v[104:105], v[56:57] op_sel_hi:[1,0]
	v_pk_mul_f32 v[74:75], v[102:103], v[56:57] op_sel_hi:[1,0]
	v_pk_mul_f32 v[72:73], v[100:101], v[56:57] op_sel_hi:[1,0]
	v_pk_mul_f32 v[70:71], v[94:95], v[56:57] op_sel_hi:[1,0]
	v_pk_mul_f32 v[68:69], v[92:93], v[56:57] op_sel_hi:[1,0]
	v_pk_mul_f32 v[66:67], v[90:91], v[56:57] op_sel_hi:[1,0]
	v_pk_mul_f32 v[64:65], v[88:89], v[56:57] op_sel_hi:[1,0]
	v_pk_mul_f32 v[54:55], v[86:87], v[56:57] op_sel_hi:[1,0]
	v_pk_mul_f32 v[52:53], v[84:85], v[56:57] op_sel_hi:[1,0]
	v_pk_mul_f32 v[6:7], v[82:83], v[56:57] op_sel_hi:[1,0]
	v_pk_mul_f32 v[4:5], v[80:81], v[56:57] op_sel_hi:[1,0]
	v_pk_mul_f32 v[62:63], v[98:99], v[56:57] op_sel_hi:[1,0]
	v_pk_mul_f32 v[60:61], v[96:97], v[56:57] op_sel_hi:[1,0]
	v_cvt_pk_bf16_f32 v56, v120, v57
	v_cvt_pk_bf16_f32 v57, v58, v59
	v_max3_f32 v59, v48, s39, v49
	v_max3_f32 v59, v59, v50, v51
	v_max3_f32 v59, v59, v12, v13
	v_max3_f32 v59, v59, v14, v15
	v_max3_f32 v59, v59, v8, v9
	v_max3_f32 v59, v59, v10, v11
	v_max3_f32 v59, v59, v0, v1
	v_max3_f32 v59, v59, v2, v3
	v_mov_b32_e32 v84, v59
	s_nop 1
	v_permlane16_swap_b32_e32 v59, v84
	v_max_f32_e32 v84, v84, v84
	v_max_f32_e32 v59, v59, v59
	v_max_f32_e32 v59, v59, v84
	v_mov_b32_e32 v84, v59
	s_nop 1
	v_permlane32_swap_b32_e32 v59, v84
	v_max3_f32 v84, v194, v59, v84
	v_sub_f32_e32 v48, v48, v84
	v_mul_f32_e32 v48, 0x3fb8aa3b, v48
	v_sub_f32_e32 v49, v49, v84
	v_exp_f32_e32 v85, v48
	v_mul_f32_e32 v49, 0x3fb8aa3b, v49
	v_exp_f32_e32 v49, v49
	v_sub_f32_e32 v50, v50, v84
	v_mul_f32_e32 v50, 0x3fb8aa3b, v50
	v_sub_f32_e32 v51, v51, v84
	v_sub_f32_e32 v12, v12, v84
	v_sub_f32_e32 v13, v13, v84
	v_add_f32_e32 v86, 0, v85
	v_exp_f32_e32 v50, v50
	v_mul_f32_e32 v51, 0x3fb8aa3b, v51
	v_mul_f32_e32 v12, 0x3fb8aa3b, v12
	v_mul_f32_e32 v13, 0x3fb8aa3b, v13
	v_exp_f32_e32 v51, v51
	v_exp_f32_e32 v87, v12
	v_add_f32_e32 v12, v49, v86
	v_exp_f32_e32 v86, v13
	v_sub_f32_e32 v13, v14, v84
	v_mul_f32_e32 v13, 0x3fb8aa3b, v13
	v_exp_f32_e32 v88, v13
	v_sub_f32_e32 v13, v15, v84
	v_sub_f32_e32 v9, v9, v84
	v_add_f32_e32 v12, v50, v12
	v_mul_f32_e32 v13, 0x3fb8aa3b, v13
	v_sub_f32_e32 v8, v8, v84
	v_mul_f32_e32 v9, 0x3fb8aa3b, v9
	v_add_f32_e32 v12, v51, v12
	v_exp_f32_e32 v89, v13
	v_mul_f32_e32 v8, 0x3fb8aa3b, v8
	v_exp_f32_e32 v91, v9
	v_sub_f32_e32 v9, v10, v84
	v_add_f32_e32 v12, v87, v12
	v_exp_f32_e32 v90, v8
	v_mul_f32_e32 v9, 0x3fb8aa3b, v9
	v_add_f32_e32 v8, v86, v12
	v_exp_f32_e32 v92, v9
	v_sub_f32_e32 v9, v11, v84
	v_sub_f32_e32 v1, v1, v84
	v_add_f32_e32 v8, v88, v8
	v_mul_f32_e32 v9, 0x3fb8aa3b, v9
	v_sub_f32_e32 v0, v0, v84
	v_mul_f32_e32 v1, 0x3fb8aa3b, v1
	v_add_f32_e32 v8, v89, v8
	v_exp_f32_e32 v93, v9
	v_mul_f32_e32 v0, 0x3fb8aa3b, v0
	v_exp_f32_e32 v95, v1
	v_sub_f32_e32 v1, v2, v84
	v_add_f32_e32 v8, v90, v8
	v_exp_f32_e32 v94, v0
	v_mul_f32_e32 v1, 0x3fb8aa3b, v1
	v_sub_f32_e32 v48, v194, v84
	v_add_f32_e32 v0, v91, v8
	v_exp_f32_e32 v96, v1
	v_sub_f32_e32 v1, v3, v84
	v_mul_f32_e32 v48, 0x3fb8aa3b, v48
	v_add_f32_e32 v0, v92, v0
	v_mul_f32_e32 v1, 0x3fb8aa3b, v1
	v_add_f32_e32 v0, v93, v0
	v_exp_f32_e32 v97, v1
	v_exp_f32_e32 v48, v48
	v_add_f32_e32 v0, v94, v0
	v_add_f32_e32 v0, v95, v0
	v_add_f32_e32 v0, v96, v0
	v_cvt_pk_bf16_f32 v58, v121, v122
	v_cvt_pk_bf16_f32 v59, v123, v134
	v_add_f32_e32 v104, v97, v0
	v_pk_mul_f32 v[2:3], v[46:47], v[48:49] op_sel_hi:[1,0]
	v_pk_mul_f32 v[0:1], v[44:45], v[48:49] op_sel_hi:[1,0]
	v_pk_mul_f32 v[10:11], v[42:43], v[48:49] op_sel_hi:[1,0]
	v_pk_mul_f32 v[8:9], v[40:41], v[48:49] op_sel_hi:[1,0]
	v_pk_mul_f32 v[14:15], v[34:35], v[48:49] op_sel_hi:[1,0]
	v_pk_mul_f32 v[12:13], v[32:33], v[48:49] op_sel_hi:[1,0]
	v_pk_mul_f32 v[30:31], v[30:31], v[48:49] op_sel_hi:[1,0]
	v_pk_mul_f32 v[28:29], v[28:29], v[48:49] op_sel_hi:[1,0]
	v_pk_mul_f32 v[26:27], v[26:27], v[48:49] op_sel_hi:[1,0]
	v_pk_mul_f32 v[24:25], v[24:25], v[48:49] op_sel_hi:[1,0]
	v_pk_mul_f32 v[22:23], v[22:23], v[48:49] op_sel_hi:[1,0]
	v_pk_mul_f32 v[20:21], v[20:21], v[48:49] op_sel_hi:[1,0]
	v_pk_mul_f32 v[34:35], v[38:39], v[48:49] op_sel_hi:[1,0]
	v_pk_mul_f32 v[32:33], v[36:37], v[48:49] op_sel_hi:[1,0]
	v_pk_mul_f32 v[18:19], v[18:19], v[48:49] op_sel_hi:[1,0]
	v_pk_mul_f32 v[16:17], v[16:17], v[48:49] op_sel_hi:[1,0]
	v_cvt_pk_bf16_f32 v36, v85, v49
	v_cvt_pk_bf16_f32 v37, v50, v51
	v_cvt_pk_bf16_f32 v38, v87, v86
	v_cvt_pk_bf16_f32 v39, v88, v89
	v_cvt_pk_bf16_f32 v80, v112, v113
	v_cvt_pk_bf16_f32 v81, v114, v115
	v_cvt_pk_bf16_f32 v82, v116, v117
	v_cvt_pk_bf16_f32 v83, v118, v119
	v_fmac_f32_e32 v104, v132, v48
	v_cvt_pk_bf16_f32 v84, v90, v91
	v_cvt_pk_bf16_f32 v85, v92, v93
	v_cvt_pk_bf16_f32 v86, v94, v95
	v_cvt_pk_bf16_f32 v87, v96, v97
	ds_read2_b64 v[40:43], v192 offset0:128 offset1:132
	s_waitcnt lgkmcnt(0)
	v_mfma_f32_16x16x32_bf16 v[44:47], v[40:43], v[80:83], v[108:111]
	v_mfma_f32_16x16x32_bf16 v[0:3], v[40:43], v[36:39], v[0:3]
	ds_read2_b64 v[40:43], v191 offset0:128 offset1:132
	s_waitcnt lgkmcnt(0)
	v_mfma_f32_16x16x32_bf16 v[48:51], v[40:43], v[80:83], v[76:79]
	v_mfma_f32_16x16x32_bf16 v[8:11], v[40:43], v[36:39], v[8:11]
	ds_read2_b64 v[40:43], v190 offset0:160 offset1:164
	s_waitcnt lgkmcnt(0)
	v_mfma_f32_16x16x32_bf16 v[72:75], v[40:43], v[80:83], v[72:75]
	v_mfma_f32_16x16x32_bf16 v[12:15], v[40:43], v[36:39], v[12:15]
	ds_read2_b64 v[40:43], v189 offset0:192 offset1:196
	s_waitcnt lgkmcnt(0)
	v_mfma_f32_16x16x32_bf16 v[76:79], v[40:43], v[36:39], v[28:31]
	s_nop 2
	ds_read2_b64 v[28:31], v188 offset1:4
	s_waitcnt lgkmcnt(0)
	v_mfma_f32_16x16x32_bf16 v[88:91], v[28:31], v[36:39], v[24:27]
	s_nop 2
	ds_read2_b64 v[24:27], v187 offset0:32 offset1:36
	s_waitcnt lgkmcnt(0)
	v_mfma_f32_16x16x32_bf16 v[92:95], v[24:27], v[80:83], v[52:55]
	v_mfma_f32_16x16x32_bf16 v[20:23], v[24:27], v[36:39], v[20:23]
	ds_read2_b64 v[24:27], v186 offset0:64 offset1:68
	s_waitcnt lgkmcnt(0)
	v_mfma_f32_16x16x32_bf16 v[4:7], v[24:27], v[80:83], v[4:7]
	v_mfma_f32_16x16x32_bf16 v[96:99], v[24:27], v[36:39], v[32:35]
	ds_read2_b64 v[24:27], v128 offset0:96 offset1:100
	s_waitcnt lgkmcnt(0)
	v_mfma_f32_16x16x32_bf16 v[100:103], v[24:27], v[36:39], v[16:19]
	s_nop 2
	ds_read2_b64 v[16:19], v192 offset0:136 offset1:140
	v_mfma_f32_16x16x32_bf16 v[68:71], v[40:43], v[80:83], v[68:71]
	v_mfma_f32_16x16x32_bf16 v[64:67], v[28:31], v[80:83], v[64:67]
	v_mfma_f32_16x16x32_bf16 v[80:83], v[24:27], v[80:83], v[60:63]
	s_waitcnt lgkmcnt(0)
	v_mfma_f32_16x16x32_bf16 v[24:27], v[16:19], v[84:87], v[0:3]
	s_nop 2
	ds_read2_b64 v[0:3], v191 offset0:136 offset1:140
	s_waitcnt lgkmcnt(0)
	v_mfma_f32_16x16x32_bf16 v[48:51], v[0:3], v[56:59], v[48:51]
	v_mfma_f32_16x16x32_bf16 v[28:31], v[0:3], v[84:87], v[8:11]
	ds_read2_b64 v[0:3], v190 offset0:168 offset1:172
	s_waitcnt lgkmcnt(0)
	v_mfma_f32_16x16x32_bf16 v[8:11], v[0:3], v[84:87], v[12:15]
	s_nop 2
	ds_read2_b64 v[12:15], v188 offset0:8 offset1:12
	s_waitcnt lgkmcnt(0)
	v_mfma_f32_16x16x32_bf16 v[52:55], v[12:15], v[56:59], v[64:67]
	s_nop 2
	v_mov_b32_e32 v64, v135
	s_nop 1
	v_permlane16_swap_b32_e32 v135, v64
	v_add_f32_e32 v64, v135, v64
	v_mov_b32_e32 v65, v64
	v_mfma_f32_16x16x32_bf16 v[40:43], v[0:3], v[56:59], v[72:75]
	ds_read2_b64 v[0:3], v189 offset0:200 offset1:204
	v_permlane32_swap_b32_e32 v64, v65
	v_add_f32_e32 v64, v64, v65
	v_div_scale_f32 v65, s[0:1], v64, v64, 1.0
	v_mfma_f32_16x16x32_bf16 v[60:63], v[16:19], v[56:59], v[44:47]
	v_rcp_f32_e32 v66, v65
	s_nop 0
	v_fma_f32 v67, -v65, v66, 1.0
	v_mfma_f32_16x16x32_bf16 v[16:19], v[12:15], v[84:87], v[88:91]
	ds_read2_b64 v[12:15], v187 offset0:40 offset1:44
	v_fmac_f32_e32 v66, v67, v66
	v_div_scale_f32 v67, vcc, 1.0, v64, 1.0
	s_waitcnt lgkmcnt(1)
	v_mfma_f32_16x16x32_bf16 v[32:35], v[0:3], v[56:59], v[68:71]
	s_nop 2
	v_mul_f32_e32 v68, v67, v66
	v_fma_f32 v69, -v65, v68, v67
	v_fmac_f32_e32 v68, v69, v66
	s_waitcnt lgkmcnt(0)
	v_mfma_f32_16x16x32_bf16 v[44:47], v[12:15], v[56:59], v[92:95]
	v_fma_f32 v65, -v65, v68, v67
	v_div_fmas_f32 v65, v65, v66, v68
	v_div_fixup_f32 v66, v65, v64, 1.0
	v_mfma_f32_16x16x32_bf16 v[12:15], v[12:15], v[84:87], v[20:23]
	v_mov_b32_e32 v64, v104
	s_nop 1
	v_permlane16_swap_b32_e32 v104, v64
	ds_read2_b64 v[20:23], v186 offset0:72 offset1:76
	v_add_f32_e32 v64, v104, v64
	v_mov_b32_e32 v65, v64
	s_nop 1
	v_permlane32_swap_b32_e32 v64, v65
	v_add_f32_e32 v64, v64, v65
	v_div_scale_f32 v65, s[0:1], v64, v64, 1.0
	s_waitcnt lgkmcnt(0)
	v_mfma_f32_16x16x32_bf16 v[36:39], v[20:23], v[56:59], v[4:7]
	v_rcp_f32_e32 v67, v65
	v_cmp_ne_u32_e64 s[0:1], 0, v185
	v_fma_f32 v68, -v65, v67, 1.0
	v_mfma_f32_16x16x32_bf16 v[4:7], v[20:23], v[84:87], v[96:99]
	ds_read2_b64 v[20:23], v128 offset0:104 offset1:108
	v_fmac_f32_e32 v67, v68, v67
	v_div_scale_f32 v68, vcc, 1.0, v64, 1.0
	v_mul_f32_e32 v69, v68, v67
	v_fma_f32 v70, -v65, v69, v68
	v_fmac_f32_e32 v69, v70, v67
	v_mfma_f32_16x16x32_bf16 v[0:3], v[0:3], v[84:87], v[76:79]
	v_fma_f32 v65, -v65, v69, v68
	v_div_fmas_f32 v65, v65, v67, v69
	v_div_fixup_f32 v64, v65, v64, 1.0
	s_waitcnt lgkmcnt(0)
	v_mfma_f32_16x16x32_bf16 v[56:59], v[20:23], v[56:59], v[80:83]
	v_lshlrev_b32_e32 v65, 2, v183
	v_cmp_eq_u32_e32 vcc, 0, v185
	v_lshl_or_b32 v65, v184, 8, v65
	v_mfma_f32_16x16x32_bf16 v[20:23], v[20:23], v[84:87], v[100:103]
	s_barrier
	s_and_saveexec_b64 s[2:3], s[0:1]
	s_cbranch_execz .LBB0_1698
	s_lshl_b32 s0, s15, 2
	v_readlane_b32 s4, v253, 26
	v_mov_b32_e32 v67, s0
	v_readlane_b32 s10, v253, 32
	v_readlane_b32 s11, v253, 33
	v_mul_f32_e32 v68, v60, v66
	v_mul_f32_e32 v69, v61, v66
	v_readlane_b32 s5, v253, 27
	v_readlane_b32 s6, v253, 28
	v_readlane_b32 s7, v253, 29
	global_load_dword v67, v67, s[10:11]
	v_readlane_b32 s8, v253, 30
	v_readlane_b32 s9, v253, 31
	v_readlane_b32 s12, v253, 34
	v_readlane_b32 s13, v253, 35
	v_readlane_b32 s14, v253, 36
	v_readlane_b32 s15, v253, 37
	v_readlane_b32 s16, v253, 38
	v_readlane_b32 s17, v253, 39
	v_readlane_b32 s18, v253, 40
	v_readlane_b32 s19, v253, 41
	s_waitcnt vmcnt(0)
	v_mul_f32_e32 v68, v67, v68
	v_mul_f32_e32 v69, v67, v69
	ds_write2st64_b32 v65, v68, v69 offset1:2
	v_mul_f32_e32 v68, v62, v66
	v_mul_f32_e32 v69, v63, v66
	v_mul_f32_e32 v68, v67, v68
	v_mul_f32_e32 v69, v67, v69
	ds_write2st64_b32 v65, v68, v69 offset0:4 offset1:6
	v_mul_f32_e32 v68, v24, v64
	v_mul_f32_e32 v69, v25, v64
	v_mul_f32_e32 v68, v67, v68
	v_mul_f32_e32 v69, v67, v69
	ds_write2st64_b32 v65, v68, v69 offset0:8 offset1:10
	v_mul_f32_e32 v68, v26, v64
	v_mul_f32_e32 v69, v27, v64
	v_mul_f32_e32 v68, v67, v68
	v_mul_f32_e32 v69, v67, v69
	ds_write2st64_b32 v65, v68, v69 offset0:12 offset1:14
	v_mul_f32_e32 v68, v48, v66
	v_mul_f32_e32 v69, v49, v66
	v_mul_f32_e32 v68, v67, v68
	v_mul_f32_e32 v69, v67, v69
	ds_write2st64_b32 v65, v68, v69 offset0:16 offset1:18
	v_mul_f32_e32 v68, v50, v66
	v_mul_f32_e32 v69, v51, v66
	v_mul_f32_e32 v68, v67, v68
	v_mul_f32_e32 v69, v67, v69
	ds_write2st64_b32 v65, v68, v69 offset0:20 offset1:22
	v_mul_f32_e32 v68, v28, v64
	v_mul_f32_e32 v69, v29, v64
	v_mul_f32_e32 v68, v67, v68
	v_mul_f32_e32 v69, v67, v69
	ds_write2st64_b32 v65, v68, v69 offset0:24 offset1:26
	v_mul_f32_e32 v68, v30, v64
	v_mul_f32_e32 v69, v31, v64
	v_mul_f32_e32 v68, v67, v68
	v_mul_f32_e32 v69, v67, v69
	ds_write2st64_b32 v65, v68, v69 offset0:28 offset1:30
	v_mul_f32_e32 v68, v40, v66
	v_mul_f32_e32 v69, v41, v66
	v_mul_f32_e32 v68, v67, v68
	v_mul_f32_e32 v69, v67, v69
	ds_write2st64_b32 v65, v68, v69 offset0:32 offset1:34
	v_mul_f32_e32 v68, v42, v66
	v_mul_f32_e32 v69, v43, v66
	v_mul_f32_e32 v68, v67, v68
	v_mul_f32_e32 v69, v67, v69
	ds_write2st64_b32 v65, v68, v69 offset0:36 offset1:38
	v_mul_f32_e32 v68, v8, v64
	v_mul_f32_e32 v69, v9, v64
	v_mul_f32_e32 v68, v67, v68
	v_mul_f32_e32 v69, v67, v69
	ds_write2st64_b32 v65, v68, v69 offset0:40 offset1:42
	v_mul_f32_e32 v68, v10, v64
	v_mul_f32_e32 v69, v11, v64
	v_mul_f32_e32 v68, v67, v68
	v_mul_f32_e32 v69, v67, v69
	ds_write2st64_b32 v65, v68, v69 offset0:44 offset1:46
	v_mul_f32_e32 v68, v32, v66
	v_mul_f32_e32 v69, v33, v66
	v_mul_f32_e32 v68, v67, v68
	v_mul_f32_e32 v69, v67, v69
	ds_write2st64_b32 v65, v68, v69 offset0:48 offset1:50
	v_mul_f32_e32 v68, v34, v66
	v_mul_f32_e32 v69, v35, v66
	v_mul_f32_e32 v68, v67, v68
	v_mul_f32_e32 v69, v67, v69
	ds_write2st64_b32 v65, v68, v69 offset0:52 offset1:54
	v_mul_f32_e32 v68, v0, v64
	v_mul_f32_e32 v69, v1, v64
	v_mul_f32_e32 v68, v67, v68
	v_mul_f32_e32 v69, v67, v69
	ds_write2st64_b32 v65, v68, v69 offset0:56 offset1:58
	v_mul_f32_e32 v68, v2, v64
	v_mul_f32_e32 v69, v3, v64
	v_mul_f32_e32 v68, v67, v68
	v_mul_f32_e32 v69, v67, v69
	ds_write2st64_b32 v65, v68, v69 offset0:60 offset1:62
	v_mul_f32_e32 v68, v52, v66
	v_mul_f32_e32 v69, v53, v66
	v_mul_f32_e32 v68, v67, v68
	v_mul_f32_e32 v69, v67, v69
	ds_write2st64_b32 v65, v68, v69 offset0:64 offset1:66
	v_mul_f32_e32 v68, v54, v66
	v_mul_f32_e32 v69, v55, v66
	v_mul_f32_e32 v68, v67, v68
	v_mul_f32_e32 v69, v67, v69
	ds_write2st64_b32 v65, v68, v69 offset0:68 offset1:70
	v_mul_f32_e32 v68, v16, v64
	v_mul_f32_e32 v69, v17, v64
	v_mul_f32_e32 v68, v67, v68
	v_mul_f32_e32 v69, v67, v69
	ds_write2st64_b32 v65, v68, v69 offset0:72 offset1:74
	v_mul_f32_e32 v68, v18, v64
	v_mul_f32_e32 v69, v19, v64
	v_mul_f32_e32 v68, v67, v68
	v_mul_f32_e32 v69, v67, v69
	ds_write2st64_b32 v65, v68, v69 offset0:76 offset1:78
	v_mul_f32_e32 v68, v44, v66
	v_mul_f32_e32 v69, v45, v66
	v_mul_f32_e32 v68, v67, v68
	v_mul_f32_e32 v69, v67, v69
	ds_write2st64_b32 v65, v68, v69 offset0:80 offset1:82
	v_mul_f32_e32 v68, v46, v66
	v_mul_f32_e32 v69, v47, v66
	v_mul_f32_e32 v68, v67, v68
	v_mul_f32_e32 v69, v67, v69
	ds_write2st64_b32 v65, v68, v69 offset0:84 offset1:86
	v_mul_f32_e32 v68, v12, v64
	v_mul_f32_e32 v69, v13, v64
	v_mul_f32_e32 v68, v67, v68
	v_mul_f32_e32 v69, v67, v69
	ds_write2st64_b32 v65, v68, v69 offset0:88 offset1:90
	v_mul_f32_e32 v68, v14, v64
	v_mul_f32_e32 v69, v15, v64
	v_mul_f32_e32 v68, v67, v68
	v_mul_f32_e32 v69, v67, v69
	ds_write2st64_b32 v65, v68, v69 offset0:92 offset1:94
	v_mul_f32_e32 v68, v36, v66
	v_mul_f32_e32 v69, v37, v66
	v_mul_f32_e32 v68, v67, v68
	v_mul_f32_e32 v69, v67, v69
	ds_write2st64_b32 v65, v68, v69 offset0:96 offset1:98
	v_mul_f32_e32 v68, v38, v66
	v_mul_f32_e32 v69, v39, v66
	v_mul_f32_e32 v68, v67, v68
	v_mul_f32_e32 v69, v67, v69
	ds_write2st64_b32 v65, v68, v69 offset0:100 offset1:102
	v_mul_f32_e32 v68, v4, v64
	v_mul_f32_e32 v69, v5, v64
	v_mul_f32_e32 v68, v67, v68
	v_mul_f32_e32 v69, v67, v69
	ds_write2st64_b32 v65, v68, v69 offset0:104 offset1:106
	v_mul_f32_e32 v68, v6, v64
	v_mul_f32_e32 v69, v7, v64
	v_mul_f32_e32 v68, v67, v68
	v_mul_f32_e32 v69, v67, v69
	ds_write2st64_b32 v65, v68, v69 offset0:108 offset1:110
	v_mul_f32_e32 v68, v56, v66
	v_mul_f32_e32 v69, v57, v66
	v_mul_f32_e32 v68, v67, v68
	v_mul_f32_e32 v69, v67, v69
	ds_write2st64_b32 v65, v68, v69 offset0:112 offset1:114
	v_mul_f32_e32 v68, v58, v66
	v_mul_f32_e32 v69, v59, v66
	v_mul_f32_e32 v68, v67, v68
	v_mul_f32_e32 v69, v67, v69
	ds_write2st64_b32 v65, v68, v69 offset0:116 offset1:118
	v_mul_f32_e32 v68, v20, v64
	v_mul_f32_e32 v69, v21, v64
	v_mul_f32_e32 v68, v67, v68
	v_mul_f32_e32 v69, v67, v69
	ds_write2st64_b32 v65, v68, v69 offset0:120 offset1:122
	v_mul_f32_e32 v68, v22, v64
	v_mul_f32_e32 v69, v23, v64
	v_mul_f32_e32 v68, v67, v68
	v_mul_f32_e32 v67, v67, v69
	ds_write2st64_b32 v65, v68, v67 offset0:124 offset1:126
